# v76 + pooling tasks balanced over the SIMDs (waves 4..7 take window groups 3,2,1,0)
# baseline (speedup 1.0000x reference)
.LBB0_651:
	v_readlane_b32 s0, v254, 50
	v_readlane_b32 s1, v254, 51
	s_andn2_b64 vcc, exec, s[0:1]
	s_cbranch_vccnz .LBB0_671
	v_mov_b32_e32 v203, 0
	v_readlane_b32 s2, v253, 6
	v_readlane_b32 s3, v253, 7
	v_or_b32_e32 v2, 0xc00, v202
	v_mov_b32_e32 v3, v203
	v_lshl_add_u64 v[96:97], s[2:3], 0, v[2:3]
	v_or_b32_e32 v2, 0x800, v202
	v_readlane_b32 s0, v254, 49
	v_lshl_add_u64 v[98:99], s[2:3], 0, v[2:3]
	v_or_b32_e32 v2, 0x400, v202
	v_lshl_add_u64 v[94:95], s[2:3], 0, v[202:203]
	s_bfe_u32 s9, s0, 0x20006
	s_bitcmp1_b32 s0, 8
	s_cselect_b32 s13, 3, 0
	s_xor_b32 s9, s9, s13
	v_lshl_add_u64 v[100:101], s[2:3], 0, v[2:3]
	v_lshl_add_u64 v[102:103], s[94:95], 0, v[202:203]
	s_mov_b32 s13, 0x27e00000
	s_mov_b32 s16, 0x27e01000
	s_mov_b32 s17, 0x27e02000
	s_mov_b32 s18, 0x27e03000
	s_mov_b32 s19, 0x27e04000
	s_mov_b32 s20, 0x27e05000
	s_mov_b32 s21, 0x27e06000
	s_mov_b32 s22, 0x27e07000
	s_mov_b32 s23, 0x3d800000
	s_mov_b32 s24, 0x200000
	s_mov_b32 s25, 0x201000
	s_mov_b32 s26, 0x202000
	s_mov_b32 s27, 0x203000
	s_mov_b32 s28, 0x204000
	s_mov_b32 s29, 0x205000
	s_mov_b32 s30, 0x206000
	s_mov_b32 s31, 0x3e000000
	s_mov_b32 s34, 0x3e800000
	s_branch .LBB0_654
